# combination of all identity trims: attention hot loop (self-max, DMA issue hoist, non-binding LDS waits merged to one per phase) and GEMM K-loop (back-edge rotation, redundant waits)
# baseline (speedup 1.0000x reference)
.LBB0_783:
	v_add_u32_e32 v0, s20, v230
	ds_read_b64_tr_b16 v[192:193], v0 offset:24576
	ds_read_b64_tr_b16 v[194:195], v0 offset:25088
	v_mfma_f32_32x32x16_bf16 v[112:127], v[188:191], v[148:151], v[48:63]
	v_add_f32_e32 v2, v80, v81
	v_add_f32_e32 v2, v82, v2
	v_add_f32_e32 v2, v83, v2
	v_add_f32_e32 v2, v84, v2
	v_add_f32_e32 v2, v85, v2
	v_cvt_pk_bf16_f32 v156, v80, v81
	v_cvt_pk_bf16_f32 v157, v82, v83
	ds_read_b64_tr_b16 v[80:81], v0 offset:28672
	ds_read_b64_tr_b16 v[82:83], v0 offset:29184
	v_mfma_f32_32x32x16_bf16 v[96:111], v[184:187], v[148:151], v[48:63]
	v_add_f32_e32 v2, v86, v2
	v_add_f32_e32 v2, v87, v2
	v_add_f32_e32 v2, v88, v2
	v_add_f32_e32 v6, v89, v2
	v_cvt_pk_bf16_f32 v158, v84, v85
	v_cvt_pk_bf16_f32 v159, v86, v87
	s_add_i32 s1, s24, s27
	s_mov_b32 m0, s1
	s_add_u32 s20, s18, 0xffe38000
	s_addc_u32 s21, s19, -1
	global_load_lds_dwordx4 v227, s[20:21]
	ds_read_b64_tr_b16 v[2:3], v0 offset:25600
	ds_read_b64_tr_b16 v[4:5], v0 offset:26112
	v_mfma_f32_32x32x16_bf16 v[112:127], v[180:183], v[136:139], v[112:127]
	v_add_f32_e32 v6, v90, v6
	v_add_f32_e32 v6, v91, v6
	v_add_f32_e32 v6, v92, v6
	v_add_f32_e32 v10, v93, v6
	v_cvt_pk_bf16_f32 v152, v88, v89
	v_cvt_pk_bf16_f32 v153, v90, v91
	ds_read_b64_tr_b16 v[6:7], v0 offset:29696
	ds_read_b64_tr_b16 v[8:9], v0 offset:30208
	v_mfma_f32_32x32x16_bf16 v[96:111], v[176:179], v[136:139], v[96:111]
	v_add_f32_e32 v10, v94, v10
	v_add_f32_e32 v10, v95, v10
	v_add_f32_e32 v10, v64, v10
	v_add_f32_e32 v14, v65, v10
	v_cvt_pk_bf16_f32 v154, v92, v93
	v_cvt_pk_bf16_f32 v155, v94, v95
	s_add_i32 s1, s2, s30
	s_mov_b32 m0, s1
	s_add_u32 s20, s16, 0xffe38000
	s_addc_u32 s21, s17, -1
	global_load_lds_dwordx4 v228, s[20:21]
	ds_read_b64_tr_b16 v[10:11], v0 offset:26624
	ds_read_b64_tr_b16 v[12:13], v0 offset:27136
	v_mfma_f32_32x32x16_bf16 v[112:127], v[172:175], v[132:135], v[112:127]
	v_add_f32_e32 v14, v66, v14
	v_add_f32_e32 v14, v67, v14
	v_add_f32_e32 v14, v68, v14
	v_add_f32_e32 v14, v69, v14
	v_cvt_pk_bf16_f32 v144, v64, v65
	v_cvt_pk_bf16_f32 v145, v66, v67
	ds_read_b64_tr_b16 v[64:65], v0 offset:30720
	ds_read_b64_tr_b16 v[66:67], v0 offset:31232
	v_mfma_f32_32x32x16_bf16 v[96:111], v[168:171], v[132:135], v[96:111]
	v_add_f32_e32 v14, v70, v14
	v_add_f32_e32 v14, v71, v14
	v_add_f32_e32 v14, v72, v14
	v_add_f32_e32 v14, v73, v14
	v_cvt_pk_bf16_f32 v146, v68, v69
	v_cvt_pk_bf16_f32 v147, v70, v71
	ds_read_b64_tr_b16 v[68:69], v0 offset:27648
	ds_read_b64_tr_b16 v[70:71], v0 offset:28160
	v_mfma_f32_32x32x16_bf16 v[112:127], v[164:167], v[128:131], v[112:127]
	v_add_f32_e32 v14, v74, v14
	v_add_f32_e32 v14, v75, v14
	v_add_f32_e32 v14, v76, v14
	v_add_f32_e32 v14, v77, v14
	v_cvt_pk_bf16_f32 v140, v72, v73
	v_cvt_pk_bf16_f32 v141, v74, v75
	ds_read_b64_tr_b16 v[72:73], v0 offset:31744
	ds_read_b64_tr_b16 v[74:75], v0 offset:32256
	v_mfma_f32_32x32x16_bf16 v[96:111], v[160:163], v[128:131], v[96:111]
	v_add_f32_e32 v0, v78, v14
	v_add_f32_e32 v0, v79, v0
	v_add_f32_e32 v0, 0, v0
	v_cvt_pk_bf16_f32 v142, v76, v77
	v_cvt_pk_bf16_f32 v143, v78, v79
	v_max_f32_e32 v14, v112, v113
	s_nop 5
	v_max3_f32 v15, v114, v115, v97
	v_max3_f32 v14, v14, v96, v98
	v_max3_f32 v14, v14, v99, v116
	v_max3_f32 v15, v15, v118, v119
	v_max3_f32 v14, v14, v117, v100
	v_max3_f32 v15, v15, v102, v103
	v_max3_f32 v14, v14, v101, v120
	v_max3_f32 v15, v15, v122, v123
	v_max3_f32 v14, v14, v121, v104
	v_max3_f32 v15, v15, v106, v107
	v_max3_f32 v14, v14, v105, v124
	v_max3_f32 v15, v15, v126, v127
	v_max3_f32 v76, v14, v125, v108
	v_max3_f32 v15, v15, v110, v111
	v_add_f32_e32 v14, v232, v0
	v_max3_f32 v0, v76, v109, v15
	v_mov_b32_e32 v15, v0
	s_nop 1
	v_permlane32_swap_b32_e32 v0, v15
	v_max_f32_e32 v0, v0, v15
	s_mov_b32 s1, 0x41000000
	v_cmp_lt_f32_e32 vcc, s1, v0
	s_cmp_lg_u64 vcc, 0
	s_cselect_b64 s[20:21], -1, 0
	s_cbranch_vccnz .LBB0_791
.LBB0_784:
	s_waitcnt lgkmcnt(0)
	v_mfma_f32_32x32x16_bf16 v[32:47], v[156:159], v[192:195], v[32:47]
	v_exp_f32_e32 v112, v112
	v_exp_f32_e32 v113, v113
	v_exp_f32_e32 v114, v114
	v_exp_f32_e32 v115, v115
	v_mfma_f32_32x32x16_bf16 v[16:31], v[156:159], v[80:83], v[16:31]
	v_exp_f32_e32 v116, v116
	v_exp_f32_e32 v117, v117
	v_exp_f32_e32 v118, v118
	v_exp_f32_e32 v119, v119
	v_add_u32_e32 v0, s2, v229
	ds_read_b128 v[76:79], v0
	ds_read_b128 v[184:187], v0 offset:512
	v_mfma_f32_32x32x16_bf16 v[32:47], v[152:155], v[2:5], v[32:47]
	v_exp_f32_e32 v120, v120
	v_exp_f32_e32 v121, v121
	v_exp_f32_e32 v122, v122
	v_exp_f32_e32 v123, v123
	ds_read_b128 v[188:191], v0 offset:2048
	ds_read_b128 v[180:183], v0 offset:2560
	v_mfma_f32_32x32x16_bf16 v[16:31], v[152:155], v[6:9], v[16:31]
	v_exp_f32_e32 v124, v124
	v_exp_f32_e32 v125, v125
	v_exp_f32_e32 v126, v126
	v_exp_f32_e32 v127, v127
	ds_read_b128 v[176:179], v0 offset:4096
	ds_read_b128 v[172:175], v0 offset:4608
	v_mfma_f32_32x32x16_bf16 v[32:47], v[144:147], v[10:13], v[32:47]
	v_exp_f32_e32 v96, v96
	v_exp_f32_e32 v97, v97
	v_exp_f32_e32 v98, v98
	v_exp_f32_e32 v99, v99
	ds_read_b128 v[168:171], v0 offset:6144
	ds_read_b128 v[164:167], v0 offset:6656
	v_mfma_f32_32x32x16_bf16 v[16:31], v[144:147], v[64:67], v[16:31]
	v_exp_f32_e32 v100, v100
	v_exp_f32_e32 v101, v101
	v_exp_f32_e32 v102, v102
	v_exp_f32_e32 v103, v103
	v_mfma_f32_32x32x16_bf16 v[32:47], v[140:143], v[68:71], v[32:47]
	v_exp_f32_e32 v104, v104
	v_exp_f32_e32 v105, v105
	v_exp_f32_e32 v106, v106
	v_exp_f32_e32 v107, v107
	v_mfma_f32_32x32x16_bf16 v[16:31], v[140:143], v[72:75], v[16:31]
	v_exp_f32_e32 v108, v108
	v_exp_f32_e32 v109, v109
	v_exp_f32_e32 v110, v110
	v_exp_f32_e32 v111, v111
	s_waitcnt vmcnt(2) lgkmcnt(0)
	s_barrier
	s_andn2_b64 vcc, exec, s[20:21]
	v_add_u32_e32 v0, s26, v231
	s_cbranch_vccnz .LBB0_786
	s_waitcnt lgkmcnt(0)
	ds_read_b128 v[2:5], v0 offset:49248
	ds_read_b128 v[6:9], v0 offset:49216
	ds_read_b128 v[10:13], v0 offset:49184
	ds_read_b128 v[64:67], v0 offset:49152
	s_waitcnt lgkmcnt(3)
	v_pk_mul_f32 v[44:45], v[44:45], v[2:3]
	s_waitcnt lgkmcnt(2)
	v_pk_mul_f32 v[40:41], v[40:41], v[6:7]
	s_waitcnt lgkmcnt(1)
	v_pk_mul_f32 v[36:37], v[36:37], v[10:11]
	v_pk_mul_f32 v[46:47], v[46:47], v[4:5]
	v_pk_mul_f32 v[42:43], v[42:43], v[8:9]
	v_pk_mul_f32 v[38:39], v[38:39], v[12:13]
	s_waitcnt lgkmcnt(0)
	v_pk_mul_f32 v[34:35], v[34:35], v[66:67]
	v_pk_mul_f32 v[32:33], v[32:33], v[64:65]
	v_pk_mul_f32 v[28:29], v[28:29], v[2:3]
	v_pk_mul_f32 v[24:25], v[24:25], v[6:7]
	v_pk_mul_f32 v[20:21], v[20:21], v[10:11]
	v_pk_mul_f32 v[30:31], v[30:31], v[4:5]
	v_pk_mul_f32 v[26:27], v[26:27], v[8:9]
	v_pk_mul_f32 v[22:23], v[22:23], v[12:13]
	v_pk_mul_f32 v[18:19], v[18:19], v[66:67]
	v_pk_mul_f32 v[16:17], v[16:17], v[64:65]
.LBB0_786:
	s_add_i32 s1, s2, 0x2000
	s_cmpk_lg_i32 s2, 0x4000
	s_cselect_b32 s34, s1, 0
	v_add_u32_e32 v15, s24, v230
	ds_read_b64_tr_b16 v[160:161], v15 offset:24576
	ds_read_b64_tr_b16 v[162:163], v15 offset:25088
	v_mfma_f32_32x32x16_bf16 v[80:95], v[76:79], v[148:151], v[48:63]
	v_add_f32_e32 v2, v112, v113
	v_add_f32_e32 v2, v114, v2
	v_add_f32_e32 v2, v115, v2
	v_add_f32_e32 v2, v116, v2
	v_add_f32_e32 v2, v117, v2
	v_cvt_pk_bf16_f32 v156, v112, v113
	v_cvt_pk_bf16_f32 v157, v114, v115
	ds_read_b64_tr_b16 v[112:113], v15 offset:28672
	ds_read_b64_tr_b16 v[114:115], v15 offset:29184
	v_mfma_f32_32x32x16_bf16 v[64:79], v[184:187], v[148:151], v[48:63]
	v_add_f32_e32 v2, v118, v2
	v_add_f32_e32 v2, v119, v2
	v_add_f32_e32 v2, v120, v2
	v_add_f32_e32 v6, v121, v2
	v_cvt_pk_bf16_f32 v158, v116, v117
	v_cvt_pk_bf16_f32 v159, v118, v119
	s_add_i32 s1, s2, s27
	s_mov_b32 m0, s1
	s_nop 0
	global_load_lds_dwordx4 v227, s[18:19]
	ds_read_b64_tr_b16 v[2:3], v15 offset:25600
	ds_read_b64_tr_b16 v[4:5], v15 offset:26112
	v_mfma_f32_32x32x16_bf16 v[80:95], v[188:191], v[136:139], v[80:95]
	v_add_f32_e32 v6, v122, v6
	v_add_f32_e32 v6, v123, v6
	v_add_f32_e32 v6, v124, v6
	v_add_f32_e32 v10, v125, v6
	v_cvt_pk_bf16_f32 v152, v120, v121
	v_cvt_pk_bf16_f32 v153, v122, v123
	ds_read_b64_tr_b16 v[6:7], v15 offset:29696
	ds_read_b64_tr_b16 v[8:9], v15 offset:30208
	v_mfma_f32_32x32x16_bf16 v[64:79], v[180:183], v[136:139], v[64:79]
	v_add_f32_e32 v10, v126, v10
	v_add_f32_e32 v10, v127, v10
	v_add_f32_e32 v10, v96, v10
	v_add_f32_e32 v116, v97, v10
	v_cvt_pk_bf16_f32 v154, v124, v125
	v_cvt_pk_bf16_f32 v155, v126, v127
	s_add_i32 s1, s34, s30
	s_mov_b32 m0, s1
	s_nop 0
	global_load_lds_dwordx4 v228, s[16:17]
	ds_read_b64_tr_b16 v[10:11], v15 offset:26624
	ds_read_b64_tr_b16 v[12:13], v15 offset:27136
	v_mfma_f32_32x32x16_bf16 v[80:95], v[176:179], v[132:135], v[80:95]
	v_add_f32_e32 v116, v98, v116
	v_add_f32_e32 v116, v99, v116
	v_add_f32_e32 v116, v100, v116
	v_add_f32_e32 v116, v101, v116
	v_cvt_pk_bf16_f32 v144, v96, v97
	v_cvt_pk_bf16_f32 v145, v98, v99
	ds_read_b64_tr_b16 v[96:97], v15 offset:30720
	ds_read_b64_tr_b16 v[98:99], v15 offset:31232
	v_mfma_f32_32x32x16_bf16 v[64:79], v[172:175], v[132:135], v[64:79]
	v_add_f32_e32 v116, v102, v116
	v_add_f32_e32 v116, v103, v116
	v_add_f32_e32 v116, v104, v116
	v_add_f32_e32 v116, v105, v116
	v_cvt_pk_bf16_f32 v146, v100, v101
	v_cvt_pk_bf16_f32 v147, v102, v103
	ds_read_b64_tr_b16 v[100:101], v15 offset:27648
	ds_read_b64_tr_b16 v[102:103], v15 offset:28160
	v_mfma_f32_32x32x16_bf16 v[80:95], v[168:171], v[128:131], v[80:95]
	v_add_f32_e32 v116, v106, v116
	v_add_f32_e32 v116, v107, v116
	v_add_f32_e32 v116, v108, v116
	v_add_f32_e32 v116, v109, v116
	v_cvt_pk_bf16_f32 v140, v104, v105
	v_cvt_pk_bf16_f32 v141, v106, v107
	ds_read_b64_tr_b16 v[104:105], v15 offset:31744
	ds_read_b64_tr_b16 v[106:107], v15 offset:32256
	v_mfma_f32_32x32x16_bf16 v[64:79], v[164:167], v[128:131], v[64:79]
	v_add_f32_e32 v15, v110, v116
	v_add_f32_e32 v15, v111, v15
	v_add_f32_e32 v15, 0, v15
	v_cvt_pk_bf16_f32 v142, v108, v109
	v_cvt_pk_bf16_f32 v143, v110, v111
	v_max_f32_e32 v108, v80, v81
	s_nop 5
	v_max3_f32 v109, v82, v83, v65
	v_max3_f32 v108, v108, v64, v66
	v_max3_f32 v108, v108, v67, v84
	v_max3_f32 v109, v109, v86, v87
	v_max3_f32 v108, v108, v85, v68
	v_max3_f32 v109, v109, v70, v71
	v_max3_f32 v108, v108, v69, v88
	v_max3_f32 v109, v109, v90, v91
	v_max3_f32 v108, v108, v89, v72
	v_max3_f32 v109, v109, v74, v75
	v_max3_f32 v108, v108, v73, v92
	v_max3_f32 v109, v109, v94, v95
	v_max3_f32 v108, v108, v93, v76
	v_max3_f32 v109, v109, v78, v79
	v_add_f32_e32 v232, v14, v15
	v_max3_f32 v14, v108, v77, v109
	v_mov_b32_e32 v15, v14
	s_nop 1
	v_permlane32_swap_b32_e32 v14, v15
	v_max_f32_e32 v14, v14, v15
	s_mov_b32 s1, 0x41000000
	v_cmp_lt_f32_e32 vcc, s1, v14
	s_cmp_lg_u64 vcc, 0
	s_cselect_b64 s[20:21], -1, 0
	s_cbranch_vccnz .LBB0_794
.LBB0_787:
	s_waitcnt lgkmcnt(0)
	v_mfma_f32_32x32x16_bf16 v[32:47], v[156:159], v[160:163], v[32:47]
	v_exp_f32_e32 v80, v80
	v_exp_f32_e32 v81, v81
	v_exp_f32_e32 v82, v82
	v_exp_f32_e32 v83, v83
	v_mfma_f32_32x32x16_bf16 v[16:31], v[156:159], v[112:115], v[16:31]
	v_exp_f32_e32 v84, v84
	v_exp_f32_e32 v85, v85
	v_exp_f32_e32 v86, v86
	v_exp_f32_e32 v87, v87
	v_add_u32_e32 v14, s34, v229
	ds_read_b128 v[188:191], v14
	ds_read_b128 v[184:187], v14 offset:512
	v_mfma_f32_32x32x16_bf16 v[32:47], v[152:155], v[2:5], v[32:47]
	v_exp_f32_e32 v88, v88
	v_exp_f32_e32 v89, v89
	v_exp_f32_e32 v90, v90
	v_exp_f32_e32 v91, v91
	ds_read_b128 v[180:183], v14 offset:2048
	ds_read_b128 v[176:179], v14 offset:2560
	v_mfma_f32_32x32x16_bf16 v[16:31], v[152:155], v[6:9], v[16:31]
	v_exp_f32_e32 v92, v92
	v_exp_f32_e32 v93, v93
	v_exp_f32_e32 v94, v94
	v_exp_f32_e32 v95, v95
	ds_read_b128 v[172:175], v14 offset:4096
	ds_read_b128 v[168:171], v14 offset:4608
	v_mfma_f32_32x32x16_bf16 v[32:47], v[144:147], v[10:13], v[32:47]
	v_exp_f32_e32 v64, v64
	v_exp_f32_e32 v65, v65
	v_exp_f32_e32 v66, v66
	v_exp_f32_e32 v67, v67
	ds_read_b128 v[164:167], v14 offset:6144
	ds_read_b128 v[160:163], v14 offset:6656
	v_mfma_f32_32x32x16_bf16 v[16:31], v[144:147], v[96:99], v[16:31]
	v_exp_f32_e32 v68, v68
	v_exp_f32_e32 v69, v69
	v_exp_f32_e32 v70, v70
	v_exp_f32_e32 v71, v71
	v_mfma_f32_32x32x16_bf16 v[32:47], v[140:143], v[100:103], v[32:47]
	v_exp_f32_e32 v72, v72
	v_exp_f32_e32 v73, v73
	v_exp_f32_e32 v74, v74
	v_exp_f32_e32 v75, v75
	v_mfma_f32_32x32x16_bf16 v[16:31], v[140:143], v[104:107], v[16:31]
	v_exp_f32_e32 v76, v76
	v_exp_f32_e32 v77, v77
	v_exp_f32_e32 v78, v78
	v_exp_f32_e32 v79, v79
	s_waitcnt vmcnt(2) lgkmcnt(0)
	s_barrier
	s_andn2_b64 vcc, exec, s[20:21]
	s_cbranch_vccnz .LBB0_789
	s_waitcnt lgkmcnt(0)
	ds_read_b128 v[2:5], v0 offset:49248
	ds_read_b128 v[6:9], v0 offset:49216
	ds_read_b128 v[10:13], v0 offset:49184
	ds_read_b128 v[96:99], v0 offset:49152
	s_waitcnt lgkmcnt(3)
	v_pk_mul_f32 v[44:45], v[44:45], v[2:3]
	s_waitcnt lgkmcnt(2)
	v_pk_mul_f32 v[40:41], v[40:41], v[6:7]
	s_waitcnt lgkmcnt(1)
	v_pk_mul_f32 v[36:37], v[36:37], v[10:11]
	v_pk_mul_f32 v[46:47], v[46:47], v[4:5]
	v_pk_mul_f32 v[42:43], v[42:43], v[8:9]
	v_pk_mul_f32 v[38:39], v[38:39], v[12:13]
	s_waitcnt lgkmcnt(0)
	v_pk_mul_f32 v[34:35], v[34:35], v[98:99]
	v_pk_mul_f32 v[32:33], v[32:33], v[96:97]
	v_pk_mul_f32 v[28:29], v[28:29], v[2:3]
	v_pk_mul_f32 v[24:25], v[24:25], v[6:7]
	v_pk_mul_f32 v[20:21], v[20:21], v[10:11]
	v_pk_mul_f32 v[30:31], v[30:31], v[4:5]
	v_pk_mul_f32 v[26:27], v[26:27], v[8:9]
	v_pk_mul_f32 v[22:23], v[22:23], v[12:13]
	v_pk_mul_f32 v[18:19], v[18:19], v[98:99]
	v_pk_mul_f32 v[16:17], v[16:17], v[96:97]

.LBB0_2404:
	v_add_u32_e32 v0, s20, v231
	ds_read_b64_tr_b16 v[192:193], v0 offset:24576
	ds_read_b64_tr_b16 v[194:195], v0 offset:25088
	v_mfma_f32_32x32x16_bf16 v[112:127], v[188:191], v[148:151], v[48:63]
	v_add_f32_e32 v2, v80, v81
	v_add_f32_e32 v2, v82, v2
	v_add_f32_e32 v2, v83, v2
	v_add_f32_e32 v2, v84, v2
	v_add_f32_e32 v2, v85, v2
	v_cvt_pk_bf16_f32 v156, v80, v81
	v_cvt_pk_bf16_f32 v157, v82, v83
	ds_read_b64_tr_b16 v[80:81], v0 offset:28672
	ds_read_b64_tr_b16 v[82:83], v0 offset:29184
	v_mfma_f32_32x32x16_bf16 v[96:111], v[184:187], v[148:151], v[48:63]
	v_add_f32_e32 v2, v86, v2
	v_add_f32_e32 v2, v87, v2
	v_add_f32_e32 v2, v88, v2
	v_add_f32_e32 v6, v89, v2
	v_cvt_pk_bf16_f32 v158, v84, v85
	v_cvt_pk_bf16_f32 v159, v86, v87
	s_add_i32 s0, s24, s27
	s_mov_b32 m0, s0
	s_add_u32 s20, s18, 0xffe38000
	s_addc_u32 s21, s19, -1
	global_load_lds_dwordx4 v228, s[20:21]
	ds_read_b64_tr_b16 v[2:3], v0 offset:25600
	ds_read_b64_tr_b16 v[4:5], v0 offset:26112
	v_mfma_f32_32x32x16_bf16 v[112:127], v[180:183], v[136:139], v[112:127]
	v_add_f32_e32 v6, v90, v6
	v_add_f32_e32 v6, v91, v6
	v_add_f32_e32 v6, v92, v6
	v_add_f32_e32 v10, v93, v6
	v_cvt_pk_bf16_f32 v152, v88, v89
	v_cvt_pk_bf16_f32 v153, v90, v91
	ds_read_b64_tr_b16 v[6:7], v0 offset:29696
	ds_read_b64_tr_b16 v[8:9], v0 offset:30208
	v_mfma_f32_32x32x16_bf16 v[96:111], v[176:179], v[136:139], v[96:111]
	v_add_f32_e32 v10, v94, v10
	v_add_f32_e32 v10, v95, v10
	v_add_f32_e32 v10, v64, v10
	v_add_f32_e32 v14, v65, v10
	v_cvt_pk_bf16_f32 v154, v92, v93
	v_cvt_pk_bf16_f32 v155, v94, v95
	s_add_i32 s0, s2, s30
	s_mov_b32 m0, s0
	s_add_u32 s20, s16, 0xffe38000
	s_addc_u32 s21, s17, -1
	global_load_lds_dwordx4 v229, s[20:21]
	ds_read_b64_tr_b16 v[10:11], v0 offset:26624
	ds_read_b64_tr_b16 v[12:13], v0 offset:27136
	v_mfma_f32_32x32x16_bf16 v[112:127], v[172:175], v[132:135], v[112:127]
	v_add_f32_e32 v14, v66, v14
	v_add_f32_e32 v14, v67, v14
	v_add_f32_e32 v14, v68, v14
	v_add_f32_e32 v14, v69, v14
	v_cvt_pk_bf16_f32 v144, v64, v65
	v_cvt_pk_bf16_f32 v145, v66, v67
	ds_read_b64_tr_b16 v[64:65], v0 offset:30720
	ds_read_b64_tr_b16 v[66:67], v0 offset:31232
	v_mfma_f32_32x32x16_bf16 v[96:111], v[168:171], v[132:135], v[96:111]
	v_add_f32_e32 v14, v70, v14
	v_add_f32_e32 v14, v71, v14
	v_add_f32_e32 v14, v72, v14
	v_add_f32_e32 v14, v73, v14
	v_cvt_pk_bf16_f32 v146, v68, v69
	v_cvt_pk_bf16_f32 v147, v70, v71
	ds_read_b64_tr_b16 v[68:69], v0 offset:27648
	ds_read_b64_tr_b16 v[70:71], v0 offset:28160
	v_mfma_f32_32x32x16_bf16 v[112:127], v[164:167], v[128:131], v[112:127]
	v_add_f32_e32 v14, v74, v14
	v_add_f32_e32 v14, v75, v14
	v_add_f32_e32 v14, v76, v14
	v_add_f32_e32 v14, v77, v14
	v_cvt_pk_bf16_f32 v140, v72, v73
	v_cvt_pk_bf16_f32 v141, v74, v75
	ds_read_b64_tr_b16 v[72:73], v0 offset:31744
	ds_read_b64_tr_b16 v[74:75], v0 offset:32256
	v_mfma_f32_32x32x16_bf16 v[96:111], v[160:163], v[128:131], v[96:111]
	v_add_f32_e32 v0, v78, v14
	v_add_f32_e32 v0, v79, v0
	v_add_f32_e32 v0, 0, v0
	v_cvt_pk_bf16_f32 v142, v76, v77
	v_cvt_pk_bf16_f32 v143, v78, v79
	v_max_f32_e32 v14, v112, v113
	s_nop 5
	v_max3_f32 v15, v114, v115, v97
	v_max3_f32 v14, v14, v96, v98
	v_max3_f32 v14, v14, v99, v116
	v_max3_f32 v15, v15, v118, v119
	v_max3_f32 v14, v14, v117, v100
	v_max3_f32 v15, v15, v102, v103
	v_max3_f32 v14, v14, v101, v120
	v_max3_f32 v15, v15, v122, v123
	v_max3_f32 v14, v14, v121, v104
	v_max3_f32 v15, v15, v106, v107
	v_max3_f32 v14, v14, v105, v124
	v_max3_f32 v15, v15, v126, v127
	v_max3_f32 v76, v14, v125, v108
	v_max3_f32 v15, v15, v110, v111
	v_add_f32_e32 v14, v233, v0
	v_max3_f32 v0, v76, v109, v15
	v_mov_b32_e32 v15, v0
	s_nop 1
	v_permlane32_swap_b32_e32 v0, v15
	v_max_f32_e32 v0, v0, v15
	v_cmp_lt_f32_e32 vcc, s49, v0
	s_cmp_lg_u64 vcc, 0
	s_cselect_b64 s[20:21], -1, 0
	s_cbranch_vccnz .LBB0_2412
.LBB0_2405:
	s_waitcnt lgkmcnt(0)
	v_mfma_f32_32x32x16_bf16 v[32:47], v[156:159], v[192:195], v[32:47]
	v_exp_f32_e32 v112, v112
	v_exp_f32_e32 v113, v113
	v_exp_f32_e32 v114, v114
	v_exp_f32_e32 v115, v115
	v_mfma_f32_32x32x16_bf16 v[16:31], v[156:159], v[80:83], v[16:31]
	v_exp_f32_e32 v116, v116
	v_exp_f32_e32 v117, v117
	v_exp_f32_e32 v118, v118
	v_exp_f32_e32 v119, v119
	v_add_u32_e32 v0, s2, v230
	ds_read_b128 v[76:79], v0
	ds_read_b128 v[184:187], v0 offset:512
	v_mfma_f32_32x32x16_bf16 v[32:47], v[152:155], v[2:5], v[32:47]
	v_exp_f32_e32 v120, v120
	v_exp_f32_e32 v121, v121
	v_exp_f32_e32 v122, v122
	v_exp_f32_e32 v123, v123
	ds_read_b128 v[188:191], v0 offset:2048
	ds_read_b128 v[180:183], v0 offset:2560
	v_mfma_f32_32x32x16_bf16 v[16:31], v[152:155], v[6:9], v[16:31]
	v_exp_f32_e32 v124, v124
	v_exp_f32_e32 v125, v125
	v_exp_f32_e32 v126, v126
	v_exp_f32_e32 v127, v127
	ds_read_b128 v[176:179], v0 offset:4096
	ds_read_b128 v[172:175], v0 offset:4608
	v_mfma_f32_32x32x16_bf16 v[32:47], v[144:147], v[10:13], v[32:47]
	v_exp_f32_e32 v96, v96
	v_exp_f32_e32 v97, v97
	v_exp_f32_e32 v98, v98
	v_exp_f32_e32 v99, v99
	ds_read_b128 v[168:171], v0 offset:6144
	ds_read_b128 v[164:167], v0 offset:6656
	v_mfma_f32_32x32x16_bf16 v[16:31], v[144:147], v[64:67], v[16:31]
	v_exp_f32_e32 v100, v100
	v_exp_f32_e32 v101, v101
	v_exp_f32_e32 v102, v102
	v_exp_f32_e32 v103, v103
	v_mfma_f32_32x32x16_bf16 v[32:47], v[140:143], v[68:71], v[32:47]
	v_exp_f32_e32 v104, v104
	v_exp_f32_e32 v105, v105
	v_exp_f32_e32 v106, v106
	v_exp_f32_e32 v107, v107
	v_mfma_f32_32x32x16_bf16 v[16:31], v[140:143], v[72:75], v[16:31]
	v_exp_f32_e32 v108, v108
	v_exp_f32_e32 v109, v109
	v_exp_f32_e32 v110, v110
	v_exp_f32_e32 v111, v111
	s_waitcnt vmcnt(2) lgkmcnt(0)
	s_barrier
	s_andn2_b64 vcc, exec, s[20:21]
	v_add_u32_e32 v0, s26, v232
	s_cbranch_vccnz .LBB0_2407
	s_waitcnt lgkmcnt(0)
	ds_read_b128 v[2:5], v0 offset:49248
	ds_read_b128 v[6:9], v0 offset:49216
	ds_read_b128 v[10:13], v0 offset:49184
	ds_read_b128 v[64:67], v0 offset:49152
	s_waitcnt lgkmcnt(3)
	v_pk_mul_f32 v[44:45], v[44:45], v[2:3]
	s_waitcnt lgkmcnt(2)
	v_pk_mul_f32 v[40:41], v[40:41], v[6:7]
	s_waitcnt lgkmcnt(1)
	v_pk_mul_f32 v[36:37], v[36:37], v[10:11]
	v_pk_mul_f32 v[46:47], v[46:47], v[4:5]
	v_pk_mul_f32 v[42:43], v[42:43], v[8:9]
	v_pk_mul_f32 v[38:39], v[38:39], v[12:13]
	s_waitcnt lgkmcnt(0)
	v_pk_mul_f32 v[34:35], v[34:35], v[66:67]
	v_pk_mul_f32 v[32:33], v[32:33], v[64:65]
	v_pk_mul_f32 v[28:29], v[28:29], v[2:3]
	v_pk_mul_f32 v[24:25], v[24:25], v[6:7]
	v_pk_mul_f32 v[20:21], v[20:21], v[10:11]
	v_pk_mul_f32 v[30:31], v[30:31], v[4:5]
	v_pk_mul_f32 v[26:27], v[26:27], v[8:9]
	v_pk_mul_f32 v[22:23], v[22:23], v[12:13]
	v_pk_mul_f32 v[18:19], v[18:19], v[66:67]
	v_pk_mul_f32 v[16:17], v[16:17], v[64:65]
.LBB0_2407:
	s_add_i32 s0, s2, 0x2000
	s_cmpk_lg_i32 s2, 0x4000
	s_cselect_b32 s34, s0, 0
	v_add_u32_e32 v15, s24, v231
	ds_read_b64_tr_b16 v[160:161], v15 offset:24576
	ds_read_b64_tr_b16 v[162:163], v15 offset:25088
	v_mfma_f32_32x32x16_bf16 v[80:95], v[76:79], v[148:151], v[48:63]
	v_add_f32_e32 v2, v112, v113
	v_add_f32_e32 v2, v114, v2
	v_add_f32_e32 v2, v115, v2
	v_add_f32_e32 v2, v116, v2
	v_add_f32_e32 v2, v117, v2
	v_cvt_pk_bf16_f32 v156, v112, v113
	v_cvt_pk_bf16_f32 v157, v114, v115
	ds_read_b64_tr_b16 v[112:113], v15 offset:28672
	ds_read_b64_tr_b16 v[114:115], v15 offset:29184
	v_mfma_f32_32x32x16_bf16 v[64:79], v[184:187], v[148:151], v[48:63]
	v_add_f32_e32 v2, v118, v2
	v_add_f32_e32 v2, v119, v2
	v_add_f32_e32 v2, v120, v2
	v_add_f32_e32 v6, v121, v2
	v_cvt_pk_bf16_f32 v158, v116, v117
	v_cvt_pk_bf16_f32 v159, v118, v119
	s_add_i32 s0, s2, s27
	s_mov_b32 m0, s0
	s_nop 0
	global_load_lds_dwordx4 v228, s[18:19]
	ds_read_b64_tr_b16 v[2:3], v15 offset:25600
	ds_read_b64_tr_b16 v[4:5], v15 offset:26112
	v_mfma_f32_32x32x16_bf16 v[80:95], v[188:191], v[136:139], v[80:95]
	v_add_f32_e32 v6, v122, v6
	v_add_f32_e32 v6, v123, v6
	v_add_f32_e32 v6, v124, v6
	v_add_f32_e32 v10, v125, v6
	v_cvt_pk_bf16_f32 v152, v120, v121
	v_cvt_pk_bf16_f32 v153, v122, v123
	ds_read_b64_tr_b16 v[6:7], v15 offset:29696
	ds_read_b64_tr_b16 v[8:9], v15 offset:30208
	v_mfma_f32_32x32x16_bf16 v[64:79], v[180:183], v[136:139], v[64:79]
	v_add_f32_e32 v10, v126, v10
	v_add_f32_e32 v10, v127, v10
	v_add_f32_e32 v10, v96, v10
	v_add_f32_e32 v116, v97, v10
	v_cvt_pk_bf16_f32 v154, v124, v125
	v_cvt_pk_bf16_f32 v155, v126, v127
	s_add_i32 s0, s34, s30
	s_mov_b32 m0, s0
	s_nop 0
	global_load_lds_dwordx4 v229, s[16:17]
	ds_read_b64_tr_b16 v[10:11], v15 offset:26624
	ds_read_b64_tr_b16 v[12:13], v15 offset:27136
	v_mfma_f32_32x32x16_bf16 v[80:95], v[176:179], v[132:135], v[80:95]
	v_add_f32_e32 v116, v98, v116
	v_add_f32_e32 v116, v99, v116
	v_add_f32_e32 v116, v100, v116
	v_add_f32_e32 v116, v101, v116
	v_cvt_pk_bf16_f32 v144, v96, v97
	v_cvt_pk_bf16_f32 v145, v98, v99
	ds_read_b64_tr_b16 v[96:97], v15 offset:30720
	ds_read_b64_tr_b16 v[98:99], v15 offset:31232
	v_mfma_f32_32x32x16_bf16 v[64:79], v[172:175], v[132:135], v[64:79]
	v_add_f32_e32 v116, v102, v116
	v_add_f32_e32 v116, v103, v116
	v_add_f32_e32 v116, v104, v116
	v_add_f32_e32 v116, v105, v116
	v_cvt_pk_bf16_f32 v146, v100, v101
	v_cvt_pk_bf16_f32 v147, v102, v103
	ds_read_b64_tr_b16 v[100:101], v15 offset:27648
	ds_read_b64_tr_b16 v[102:103], v15 offset:28160
	v_mfma_f32_32x32x16_bf16 v[80:95], v[168:171], v[128:131], v[80:95]
	v_add_f32_e32 v116, v106, v116
	v_add_f32_e32 v116, v107, v116
	v_add_f32_e32 v116, v108, v116
	v_add_f32_e32 v116, v109, v116
	v_cvt_pk_bf16_f32 v140, v104, v105
	v_cvt_pk_bf16_f32 v141, v106, v107
	ds_read_b64_tr_b16 v[104:105], v15 offset:31744
	ds_read_b64_tr_b16 v[106:107], v15 offset:32256
	v_mfma_f32_32x32x16_bf16 v[64:79], v[164:167], v[128:131], v[64:79]
	v_add_f32_e32 v15, v110, v116
	v_add_f32_e32 v15, v111, v15
	v_add_f32_e32 v15, 0, v15
	v_cvt_pk_bf16_f32 v142, v108, v109
	v_cvt_pk_bf16_f32 v143, v110, v111
	v_max_f32_e32 v108, v80, v81
	s_nop 5
	v_max3_f32 v109, v82, v83, v65
	v_max3_f32 v108, v108, v64, v66
	v_max3_f32 v108, v108, v67, v84
	v_max3_f32 v109, v109, v86, v87
	v_max3_f32 v108, v108, v85, v68
	v_max3_f32 v109, v109, v70, v71
	v_max3_f32 v108, v108, v69, v88
	v_max3_f32 v109, v109, v90, v91
	v_max3_f32 v108, v108, v89, v72
	v_max3_f32 v109, v109, v74, v75
	v_max3_f32 v108, v108, v73, v92
	v_max3_f32 v109, v109, v94, v95
	v_max3_f32 v108, v108, v93, v76
	v_max3_f32 v109, v109, v78, v79
	v_add_f32_e32 v233, v14, v15
	v_max3_f32 v14, v108, v77, v109
	v_mov_b32_e32 v15, v14
	s_nop 1
	v_permlane32_swap_b32_e32 v14, v15
	v_max_f32_e32 v14, v14, v15
	v_cmp_lt_f32_e32 vcc, s49, v14
	s_cmp_lg_u64 vcc, 0
	s_cselect_b64 s[20:21], -1, 0
	s_cbranch_vccnz .LBB0_2415
.LBB0_2408:
	s_waitcnt lgkmcnt(0)
	v_mfma_f32_32x32x16_bf16 v[32:47], v[156:159], v[160:163], v[32:47]
	v_exp_f32_e32 v80, v80
	v_exp_f32_e32 v81, v81
	v_exp_f32_e32 v82, v82
	v_exp_f32_e32 v83, v83
	v_mfma_f32_32x32x16_bf16 v[16:31], v[156:159], v[112:115], v[16:31]
	v_exp_f32_e32 v84, v84
	v_exp_f32_e32 v85, v85
	v_exp_f32_e32 v86, v86
	v_exp_f32_e32 v87, v87
	v_add_u32_e32 v14, s34, v230
	ds_read_b128 v[188:191], v14
	ds_read_b128 v[184:187], v14 offset:512
	v_mfma_f32_32x32x16_bf16 v[32:47], v[152:155], v[2:5], v[32:47]
	v_exp_f32_e32 v88, v88
	v_exp_f32_e32 v89, v89
	v_exp_f32_e32 v90, v90
	v_exp_f32_e32 v91, v91
	ds_read_b128 v[180:183], v14 offset:2048
	ds_read_b128 v[176:179], v14 offset:2560
	v_mfma_f32_32x32x16_bf16 v[16:31], v[152:155], v[6:9], v[16:31]
	v_exp_f32_e32 v92, v92
	v_exp_f32_e32 v93, v93
	v_exp_f32_e32 v94, v94
	v_exp_f32_e32 v95, v95
	ds_read_b128 v[172:175], v14 offset:4096
	ds_read_b128 v[168:171], v14 offset:4608
	v_mfma_f32_32x32x16_bf16 v[32:47], v[144:147], v[10:13], v[32:47]
	v_exp_f32_e32 v64, v64
	v_exp_f32_e32 v65, v65
	v_exp_f32_e32 v66, v66
	v_exp_f32_e32 v67, v67
	ds_read_b128 v[164:167], v14 offset:6144
	ds_read_b128 v[160:163], v14 offset:6656
	v_mfma_f32_32x32x16_bf16 v[16:31], v[144:147], v[96:99], v[16:31]
	v_exp_f32_e32 v68, v68
	v_exp_f32_e32 v69, v69
	v_exp_f32_e32 v70, v70
	v_exp_f32_e32 v71, v71
	v_mfma_f32_32x32x16_bf16 v[32:47], v[140:143], v[100:103], v[32:47]
	v_exp_f32_e32 v72, v72
	v_exp_f32_e32 v73, v73
	v_exp_f32_e32 v74, v74
	v_exp_f32_e32 v75, v75
	v_mfma_f32_32x32x16_bf16 v[16:31], v[140:143], v[104:107], v[16:31]
	v_exp_f32_e32 v76, v76
	v_exp_f32_e32 v77, v77
	v_exp_f32_e32 v78, v78
	v_exp_f32_e32 v79, v79
	s_waitcnt vmcnt(2) lgkmcnt(0)
	s_barrier
	s_andn2_b64 vcc, exec, s[20:21]
	s_cbranch_vccnz .LBB0_2410
	s_waitcnt lgkmcnt(0)
	ds_read_b128 v[2:5], v0 offset:49248
	ds_read_b128 v[6:9], v0 offset:49216
	ds_read_b128 v[10:13], v0 offset:49184
	ds_read_b128 v[96:99], v0 offset:49152
	s_waitcnt lgkmcnt(3)
	v_pk_mul_f32 v[44:45], v[44:45], v[2:3]
	s_waitcnt lgkmcnt(2)
	v_pk_mul_f32 v[40:41], v[40:41], v[6:7]
	s_waitcnt lgkmcnt(1)
	v_pk_mul_f32 v[36:37], v[36:37], v[10:11]
	v_pk_mul_f32 v[46:47], v[46:47], v[4:5]
	v_pk_mul_f32 v[42:43], v[42:43], v[8:9]
	v_pk_mul_f32 v[38:39], v[38:39], v[12:13]
	s_waitcnt lgkmcnt(0)
	v_pk_mul_f32 v[34:35], v[34:35], v[98:99]
	v_pk_mul_f32 v[32:33], v[32:33], v[96:97]
	v_pk_mul_f32 v[28:29], v[28:29], v[2:3]
	v_pk_mul_f32 v[24:25], v[24:25], v[6:7]
	v_pk_mul_f32 v[20:21], v[20:21], v[10:11]
	v_pk_mul_f32 v[30:31], v[30:31], v[4:5]
	v_pk_mul_f32 v[26:27], v[26:27], v[8:9]
	v_pk_mul_f32 v[22:23], v[22:23], v[12:13]
	v_pk_mul_f32 v[18:19], v[18:19], v[98:99]
	v_pk_mul_f32 v[16:17], v[16:17], v[96:97]
